# delta-rule solve: wait gaps between dependent f32 MFMA groups tightened from 16 to 12 states (10 required)
# baseline (speedup 1.0000x reference)
.Ldm_not:
	s_waitcnt lgkmcnt(0)
	s_barrier
	v_lshlrev_b32_e32 v211, 8, v201
	v_lshl_add_u32 v211, v210, 4, v211
	v_add_u32_e32 v211, 0x17c00, v211
	v_lshlrev_b32_e32 v212, 6, v201
	v_lshl_add_u32 v212, v210, 4, v212
	v_add_u32_e32 v212, 0x24800, v212
	ds_read_b128 v[36:39], v212
	ds_read_b128 v[40:43], v212 offset:1024
	ds_read_b128 v[44:47], v212 offset:2048
	ds_read_b128 v[86:89], v212 offset:3072
	ds_read_b128 v[168:171], v211 offset:4096
	ds_read_b128 v[172:175], v211 offset:8192
	ds_read_b128 v[176:179], v211 offset:8256
	ds_read_b128 v[180:183], v211 offset:12288
	ds_read_b128 v[184:187], v211 offset:12352
	ds_read_b128 v[32:35], v211 offset:12416
	v_mov_b32_e32 v136, 0
	v_mov_b32_e32 v137, 0
	v_mov_b32_e32 v138, 0
	v_mov_b32_e32 v139, 0
	v_mov_b32_e32 v140, 0
	v_mov_b32_e32 v141, 0
	v_mov_b32_e32 v142, 0
	v_mov_b32_e32 v143, 0
	v_mov_b32_e32 v144, 0
	v_mov_b32_e32 v145, 0
	v_mov_b32_e32 v146, 0
	v_mov_b32_e32 v147, 0
	v_mov_b32_e32 v148, 0
	v_mov_b32_e32 v149, 0
	v_mov_b32_e32 v150, 0
	v_mov_b32_e32 v151, 0
	v_mov_b32_e32 v152, 0
	v_mov_b32_e32 v153, 0
	v_mov_b32_e32 v154, 0
	v_mov_b32_e32 v155, 0
	v_mov_b32_e32 v156, 0
	v_mov_b32_e32 v157, 0
	v_mov_b32_e32 v158, 0
	v_mov_b32_e32 v159, 0
	v_mov_b32_e32 v160, 0
	v_mov_b32_e32 v161, 0
	v_mov_b32_e32 v162, 0
	v_mov_b32_e32 v163, 0
	v_mov_b32_e32 v164, 0
	v_mov_b32_e32 v165, 0
	v_mov_b32_e32 v166, 0
	v_mov_b32_e32 v167, 0
	s_waitcnt lgkmcnt(0)
	v_mfma_f32_16x16x4_f32 v[136:139], v36, v104, v[136:139]
	v_mfma_f32_16x16x4_f32 v[140:143], v36, v108, v[140:143]
	v_mfma_f32_16x16x4_f32 v[136:139], v37, v105, v[136:139]
	v_mfma_f32_16x16x4_f32 v[140:143], v37, v109, v[140:143]
	v_mfma_f32_16x16x4_f32 v[136:139], v38, v106, v[136:139]
	v_mfma_f32_16x16x4_f32 v[140:143], v38, v110, v[140:143]
	v_mfma_f32_16x16x4_f32 v[136:139], v39, v107, v[136:139]
	v_mfma_f32_16x16x4_f32 v[140:143], v39, v111, v[140:143]
	s_nop 7
	s_nop 3
	v_mfma_f32_16x16x4_f32 v[112:115], v168, v136, v[112:115]
	v_mfma_f32_16x16x4_f32 v[116:119], v168, v140, v[116:119]
	v_mfma_f32_16x16x4_f32 v[112:115], v169, v137, v[112:115]
	v_mfma_f32_16x16x4_f32 v[116:119], v169, v141, v[116:119]
	v_mfma_f32_16x16x4_f32 v[112:115], v170, v138, v[112:115]
	v_mfma_f32_16x16x4_f32 v[116:119], v170, v142, v[116:119]
	v_mfma_f32_16x16x4_f32 v[112:115], v171, v139, v[112:115]
	v_mfma_f32_16x16x4_f32 v[116:119], v171, v143, v[116:119]
	s_nop 7
	s_nop 3
	v_mfma_f32_16x16x4_f32 v[144:147], v40, v112, v[144:147]
	v_mfma_f32_16x16x4_f32 v[148:151], v40, v116, v[148:151]
	v_mfma_f32_16x16x4_f32 v[144:147], v41, v113, v[144:147]
	v_mfma_f32_16x16x4_f32 v[148:151], v41, v117, v[148:151]
	v_mfma_f32_16x16x4_f32 v[144:147], v42, v114, v[144:147]
	v_mfma_f32_16x16x4_f32 v[148:151], v42, v118, v[148:151]
	v_mfma_f32_16x16x4_f32 v[144:147], v43, v115, v[144:147]
	v_mfma_f32_16x16x4_f32 v[148:151], v43, v119, v[148:151]
	s_nop 7
	s_nop 3
	v_mfma_f32_16x16x4_f32 v[120:123], v172, v136, v[120:123]
	v_mfma_f32_16x16x4_f32 v[124:127], v172, v140, v[124:127]
	v_mfma_f32_16x16x4_f32 v[120:123], v173, v137, v[120:123]
	v_mfma_f32_16x16x4_f32 v[124:127], v173, v141, v[124:127]
	v_mfma_f32_16x16x4_f32 v[120:123], v174, v138, v[120:123]
	v_mfma_f32_16x16x4_f32 v[124:127], v174, v142, v[124:127]
	v_mfma_f32_16x16x4_f32 v[120:123], v175, v139, v[120:123]
	v_mfma_f32_16x16x4_f32 v[124:127], v175, v143, v[124:127]
	v_mfma_f32_16x16x4_f32 v[120:123], v176, v144, v[120:123]
	v_mfma_f32_16x16x4_f32 v[124:127], v176, v148, v[124:127]
	v_mfma_f32_16x16x4_f32 v[120:123], v177, v145, v[120:123]
	v_mfma_f32_16x16x4_f32 v[124:127], v177, v149, v[124:127]
	v_mfma_f32_16x16x4_f32 v[120:123], v178, v146, v[120:123]
	v_mfma_f32_16x16x4_f32 v[124:127], v178, v150, v[124:127]
	v_mfma_f32_16x16x4_f32 v[120:123], v179, v147, v[120:123]
	v_mfma_f32_16x16x4_f32 v[124:127], v179, v151, v[124:127]
	s_nop 7
	s_nop 3
	v_mfma_f32_16x16x4_f32 v[152:155], v44, v120, v[152:155]
	v_mfma_f32_16x16x4_f32 v[156:159], v44, v124, v[156:159]
	v_mfma_f32_16x16x4_f32 v[152:155], v45, v121, v[152:155]
	v_mfma_f32_16x16x4_f32 v[156:159], v45, v125, v[156:159]
	v_mfma_f32_16x16x4_f32 v[152:155], v46, v122, v[152:155]
	v_mfma_f32_16x16x4_f32 v[156:159], v46, v126, v[156:159]
	v_mfma_f32_16x16x4_f32 v[152:155], v47, v123, v[152:155]
	v_mfma_f32_16x16x4_f32 v[156:159], v47, v127, v[156:159]
	s_nop 7
	s_nop 3
	v_mfma_f32_16x16x4_f32 v[128:131], v180, v136, v[128:131]
	v_mfma_f32_16x16x4_f32 v[132:135], v180, v140, v[132:135]
	v_mfma_f32_16x16x4_f32 v[128:131], v181, v137, v[128:131]
	v_mfma_f32_16x16x4_f32 v[132:135], v181, v141, v[132:135]
	v_mfma_f32_16x16x4_f32 v[128:131], v182, v138, v[128:131]
	v_mfma_f32_16x16x4_f32 v[132:135], v182, v142, v[132:135]
	v_mfma_f32_16x16x4_f32 v[128:131], v183, v139, v[128:131]
	v_mfma_f32_16x16x4_f32 v[132:135], v183, v143, v[132:135]
	v_mfma_f32_16x16x4_f32 v[128:131], v184, v144, v[128:131]
	v_mfma_f32_16x16x4_f32 v[132:135], v184, v148, v[132:135]
	v_mfma_f32_16x16x4_f32 v[128:131], v185, v145, v[128:131]
	v_mfma_f32_16x16x4_f32 v[132:135], v185, v149, v[132:135]
	v_mfma_f32_16x16x4_f32 v[128:131], v186, v146, v[128:131]
	v_mfma_f32_16x16x4_f32 v[132:135], v186, v150, v[132:135]
	v_mfma_f32_16x16x4_f32 v[128:131], v187, v147, v[128:131]
	v_mfma_f32_16x16x4_f32 v[132:135], v187, v151, v[132:135]
	v_mfma_f32_16x16x4_f32 v[128:131], v32, v152, v[128:131]
	v_mfma_f32_16x16x4_f32 v[132:135], v32, v156, v[132:135]
	v_mfma_f32_16x16x4_f32 v[128:131], v33, v153, v[128:131]
	v_mfma_f32_16x16x4_f32 v[132:135], v33, v157, v[132:135]
	v_mfma_f32_16x16x4_f32 v[128:131], v34, v154, v[128:131]
	v_mfma_f32_16x16x4_f32 v[132:135], v34, v158, v[132:135]
	v_mfma_f32_16x16x4_f32 v[128:131], v35, v155, v[128:131]
	v_mfma_f32_16x16x4_f32 v[132:135], v35, v159, v[132:135]
	s_nop 7
	s_nop 3
	v_mfma_f32_16x16x4_f32 v[160:163], v86, v128, v[160:163]
	v_mfma_f32_16x16x4_f32 v[164:167], v86, v132, v[164:167]
	v_mfma_f32_16x16x4_f32 v[160:163], v87, v129, v[160:163]
	v_mfma_f32_16x16x4_f32 v[164:167], v87, v133, v[164:167]
	v_mfma_f32_16x16x4_f32 v[160:163], v88, v130, v[160:163]
	v_mfma_f32_16x16x4_f32 v[164:167], v88, v134, v[164:167]
	v_mfma_f32_16x16x4_f32 v[160:163], v89, v131, v[160:163]
	v_mfma_f32_16x16x4_f32 v[164:167], v89, v135, v[164:167]
	s_nop 7
	s_nop 3
	s_cmp_ge_u32 s91, 4
	v_cvt_pk_bf16_f32 v213, v136, 0
	v_cvt_pk_bf16_f32 v214, v137, 0
	v_cvt_pk_bf16_f32 v215, v138, 0
	v_cvt_pk_bf16_f32 v216, v139, 0
	v_cvt_pk_bf16_f32 v217, v140, 0
	v_cvt_pk_bf16_f32 v218, v141, 0
	v_cvt_pk_bf16_f32 v219, v142, 0
	v_cvt_pk_bf16_f32 v220, v143, 0
	v_cvt_pk_bf16_f32 v221, v144, 0
	v_cvt_pk_bf16_f32 v222, v145, 0
	v_cvt_pk_bf16_f32 v223, v146, 0
	v_cvt_pk_bf16_f32 v224, v147, 0
	v_cvt_pk_bf16_f32 v225, v148, 0
	v_cvt_pk_bf16_f32 v226, v149, 0
	v_cvt_pk_bf16_f32 v227, v150, 0
	v_cvt_pk_bf16_f32 v228, v151, 0
	v_cvt_pk_bf16_f32 v229, v152, 0
	v_cvt_pk_bf16_f32 v230, v153, 0
	v_cvt_pk_bf16_f32 v231, v154, 0
	v_cvt_pk_bf16_f32 v232, v155, 0
	v_cvt_pk_bf16_f32 v233, v156, 0
	v_cvt_pk_bf16_f32 v234, v157, 0
	v_cvt_pk_bf16_f32 v235, v158, 0
	v_cvt_pk_bf16_f32 v236, v159, 0
	v_cvt_pk_bf16_f32 v237, v160, 0
	v_cvt_pk_bf16_f32 v238, v161, 0
	v_cvt_pk_bf16_f32 v239, v162, 0
	v_cvt_pk_bf16_f32 v240, v163, 0
	v_cvt_pk_bf16_f32 v241, v164, 0
	v_cvt_pk_bf16_f32 v242, v165, 0
	v_cvt_pk_bf16_f32 v243, v166, 0
	v_cvt_pk_bf16_f32 v244, v167, 0
	s_cbranch_scc1 .Ldm_kout
	ds_write_b16 v245, v213
	ds_write_b16 v245, v214 offset:256
	ds_write_b16 v245, v215 offset:512
	ds_write_b16 v245, v216 offset:768
	ds_write_b16 v245, v217 offset:32
	ds_write_b16 v245, v218 offset:288
	ds_write_b16 v245, v219 offset:544
	ds_write_b16 v245, v220 offset:800
	s_waitcnt lgkmcnt(7)
	ds_write_b16 v245, v221 offset:4096
	ds_write_b16 v245, v222 offset:4352
	ds_write_b16 v245, v223 offset:4608
	ds_write_b16 v245, v224 offset:4864
	ds_write_b16 v245, v225 offset:4128
	ds_write_b16 v245, v226 offset:4384
	ds_write_b16 v245, v227 offset:4640
	ds_write_b16 v245, v228 offset:4896
	s_waitcnt lgkmcnt(7)
	ds_write_b16 v245, v229 offset:8192
	ds_write_b16 v245, v230 offset:8448
	ds_write_b16 v245, v231 offset:8704
	ds_write_b16 v245, v232 offset:8960
	ds_write_b16 v245, v233 offset:8224
	ds_write_b16 v245, v234 offset:8480
	ds_write_b16 v245, v235 offset:8736
	ds_write_b16 v245, v236 offset:8992
	s_waitcnt lgkmcnt(7)
	ds_write_b16 v245, v237 offset:12288
	ds_write_b16 v245, v238 offset:12544
	ds_write_b16 v245, v239 offset:12800
	ds_write_b16 v245, v240 offset:13056
	ds_write_b16 v245, v241 offset:12320
	ds_write_b16 v245, v242 offset:12576
	ds_write_b16 v245, v243 offset:12832
	ds_write_b16 v245, v244 offset:13088
	s_waitcnt lgkmcnt(7)
	s_branch .Ldm_done
